# v45 + same loop-invariant LDS address hoist in the w_in (bf16 and int8) and w_out K-loops: no VALU left in any GEMM K-loop
# baseline (speedup 1.0000x reference)
.LBB0_815:
	s_lshl_b32 s12, s61, 20
	s_and_b64 s[64:65], s[4:5], exec
	s_cselect_b32 s64, s12, s66
	s_lshl_b32 s13, s60, 20
	s_and_b64 s[76:77], s[4:5], exec
	v_mov_b32_e32 v2, 0
	s_cselect_b32 s65, s13, s67
	s_add_i32 s66, s66, 0x80080
	s_addk_i32 s67, 0x100
	s_mov_b32 s76, -2
	v_mov_b32_e32 v3, v2
	v_mov_b32_e32 v4, v2
	v_mov_b32_e32 v5, v2
	v_mov_b32_e32 v6, v2
	v_mov_b32_e32 v7, v2
	v_mov_b32_e32 v8, v2
	v_mov_b32_e32 v9, v2
	v_mov_b32_e32 v10, v2
	v_mov_b32_e32 v11, v2
	v_mov_b32_e32 v12, v2
	v_mov_b32_e32 v13, v2
	v_mov_b32_e32 v18, v2
	v_mov_b32_e32 v19, v2
	v_mov_b32_e32 v20, v2
	v_mov_b32_e32 v21, v2
	v_mov_b32_e32 v26, v2
	v_mov_b32_e32 v27, v2
	v_mov_b32_e32 v28, v2
	v_mov_b32_e32 v29, v2
	v_mov_b32_e32 v34, v2
	v_mov_b32_e32 v35, v2
	v_mov_b32_e32 v36, v2
	v_mov_b32_e32 v37, v2
	v_mov_b32_e32 v42, v2
	v_mov_b32_e32 v43, v2
	v_mov_b32_e32 v44, v2
	v_mov_b32_e32 v45, v2
	v_mov_b32_e32 v50, v2
	v_mov_b32_e32 v51, v2
	v_mov_b32_e32 v52, v2
	v_mov_b32_e32 v53, v2
	v_mov_b32_e32 v14, v2
	v_mov_b32_e32 v15, v2
	v_mov_b32_e32 v16, v2
	v_mov_b32_e32 v17, v2
	v_mov_b32_e32 v22, v2
	v_mov_b32_e32 v23, v2
	v_mov_b32_e32 v24, v2
	v_mov_b32_e32 v25, v2
	v_mov_b32_e32 v30, v2
	v_mov_b32_e32 v31, v2
	v_mov_b32_e32 v32, v2
	v_mov_b32_e32 v33, v2
	v_mov_b32_e32 v38, v2
	v_mov_b32_e32 v39, v2
	v_mov_b32_e32 v40, v2
	v_mov_b32_e32 v41, v2
	v_mov_b32_e32 v46, v2
	v_mov_b32_e32 v47, v2
	v_mov_b32_e32 v48, v2
	v_mov_b32_e32 v49, v2
	v_mov_b32_e32 v54, v2
	v_mov_b32_e32 v55, v2
	v_mov_b32_e32 v56, v2
	v_mov_b32_e32 v57, v2
	v_mov_b32_e32 v58, v2
	v_mov_b32_e32 v59, v2
	v_mov_b32_e32 v60, v2
	v_mov_b32_e32 v61, v2
	v_mov_b32_e32 v62, v2
	v_mov_b32_e32 v63, v2
	v_mov_b32_e32 v64, v2
	v_mov_b32_e32 v65, v2
	v_mov_b32_e32 v66, v2
	v_mov_b32_e32 v67, v2
	v_mov_b32_e32 v68, v2
	v_mov_b32_e32 v69, v2
	v_mov_b32_e32 v70, v2
	v_mov_b32_e32 v71, v2
	v_mov_b32_e32 v72, v2
	v_mov_b32_e32 v73, v2
	v_mov_b32_e32 v74, v2
	v_mov_b32_e32 v75, v2
	v_mov_b32_e32 v76, v2
	v_mov_b32_e32 v77, v2
	v_mov_b32_e32 v82, v2
	v_mov_b32_e32 v83, v2
	v_mov_b32_e32 v84, v2
	v_mov_b32_e32 v85, v2
	v_mov_b32_e32 v90, v2
	v_mov_b32_e32 v91, v2
	v_mov_b32_e32 v92, v2
	v_mov_b32_e32 v93, v2
	v_mov_b32_e32 v98, v2
	v_mov_b32_e32 v99, v2
	v_mov_b32_e32 v100, v2
	v_mov_b32_e32 v101, v2
	v_mov_b32_e32 v106, v2
	v_mov_b32_e32 v107, v2
	v_mov_b32_e32 v108, v2
	v_mov_b32_e32 v109, v2
	v_mov_b32_e32 v114, v2
	v_mov_b32_e32 v115, v2
	v_mov_b32_e32 v116, v2
	v_mov_b32_e32 v117, v2
	v_mov_b32_e32 v78, v2
	v_mov_b32_e32 v79, v2
	v_mov_b32_e32 v80, v2
	v_mov_b32_e32 v81, v2
	v_mov_b32_e32 v86, v2
	v_mov_b32_e32 v87, v2
	v_mov_b32_e32 v88, v2
	v_mov_b32_e32 v89, v2
	v_mov_b32_e32 v94, v2
	v_mov_b32_e32 v95, v2
	v_mov_b32_e32 v96, v2
	v_mov_b32_e32 v97, v2
	v_mov_b32_e32 v102, v2
	v_mov_b32_e32 v103, v2
	v_mov_b32_e32 v104, v2
	v_mov_b32_e32 v105, v2
	v_mov_b32_e32 v110, v2
	v_mov_b32_e32 v111, v2
	v_mov_b32_e32 v112, v2
	v_mov_b32_e32 v113, v2
	v_mov_b32_e32 v118, v2
	v_mov_b32_e32 v119, v2
	v_mov_b32_e32 v120, v2
	v_mov_b32_e32 v121, v2
	v_mov_b32_e32 v122, v2
	v_mov_b32_e32 v123, v2
	v_mov_b32_e32 v124, v2
	v_mov_b32_e32 v125, v2
	v_mov_b32_e32 v126, v2
	v_mov_b32_e32 v127, v2
	v_mov_b32_e32 v128, v2
	v_mov_b32_e32 v129, v2
	v_add_u32_e32 v218, 0x10000, v155
	v_add_u32_e32 v219, 0x14000, v155
	v_add_u32_e32 v220, 0x18000, v155
	v_add_u32_e32 v221, 0x1c000, v155
.LBB0_816:
	ds_read_b128 v[134:137], v218
	ds_read_b128 v[158:161], v218 offset:1024
	ds_read_b128 v[162:165], v218 offset:2048
	ds_read_b128 v[166:169], v218 offset:3072
	ds_read_b128 v[170:173], v219
	ds_read_b128 v[174:177], v219 offset:1024
	ds_read_b128 v[178:181], v219 offset:2048
	ds_read_b128 v[182:185], v219 offset:3072
	s_add_i32 s47, s66, 0xfff80080
	s_cmp_eq_u32 s76, 28
	s_cselect_b32 s79, s64, s47
	s_cselect_b32 s78, s65, s67
	s_or_b32 s77, s79, 0x80
	s_mov_b32 s47, s31
	s_mov_b32 m0, s53
	ds_read_b128 v[186:189], v156
	ds_read_b128 v[190:193], v156 offset:1024
	ds_read_b128 v[194:197], v156 offset:2048
	ds_read_b128 v[198:201], v156 offset:3072
	ds_read_b128 v[202:205], v156 offset:4096
	ds_read_b128 v[206:209], v156 offset:5120
	ds_read_b128 v[210:213], v156 offset:6144
	ds_read_b128 v[214:217], v156 offset:7168
	buffer_load_dwordx4 v131, s[44:47], s66 offen lds
	s_mov_b32 m0, s56
	s_nop 0
	buffer_load_dwordx4 v150, s[44:47], s66 offen lds
	s_waitcnt vmcnt(8)
	s_waitcnt lgkmcnt(0)
	s_barrier
	s_setprio 1
	s_waitcnt lgkmcnt(7)
	v_mfma_f32_16x16x32_bf16 v[126:129], v[134:137], v[186:189], v[126:129]
	v_mfma_f32_16x16x32_bf16 v[122:125], v[162:165], v[186:189], v[122:125]
	s_waitcnt lgkmcnt(5)
	v_mfma_f32_16x16x32_bf16 v[118:121], v[134:137], v[194:197], v[118:121]
	v_mfma_f32_16x16x32_bf16 v[110:113], v[162:165], v[194:197], v[110:113]
	s_waitcnt lgkmcnt(3)
	v_mfma_f32_16x16x32_bf16 v[102:105], v[134:137], v[202:205], v[102:105]
	v_mfma_f32_16x16x32_bf16 v[94:97], v[162:165], v[202:205], v[94:97]
	s_waitcnt lgkmcnt(1)
	v_mfma_f32_16x16x32_bf16 v[86:89], v[134:137], v[210:213], v[86:89]
	v_mfma_f32_16x16x32_bf16 v[78:81], v[162:165], v[210:213], v[78:81]
	v_mfma_f32_16x16x32_bf16 v[126:129], v[158:161], v[190:193], v[126:129]
	v_mfma_f32_16x16x32_bf16 v[122:125], v[166:169], v[190:193], v[122:125]
	v_mfma_f32_16x16x32_bf16 v[118:121], v[158:161], v[198:201], v[118:121]
	v_mfma_f32_16x16x32_bf16 v[110:113], v[166:169], v[198:201], v[110:113]
	v_mfma_f32_16x16x32_bf16 v[102:105], v[158:161], v[206:209], v[102:105]
	v_mfma_f32_16x16x32_bf16 v[94:97], v[166:169], v[206:209], v[94:97]
	s_waitcnt lgkmcnt(0)
	v_mfma_f32_16x16x32_bf16 v[86:89], v[158:161], v[214:217], v[86:89]
	v_mfma_f32_16x16x32_bf16 v[78:81], v[166:169], v[214:217], v[78:81]
	s_setprio 0
	s_setprio 1
	v_mfma_f32_16x16x32_bf16 v[114:117], v[170:173], v[186:189], v[114:117]
	v_mfma_f32_16x16x32_bf16 v[106:109], v[178:181], v[186:189], v[106:109]
	v_mfma_f32_16x16x32_bf16 v[98:101], v[170:173], v[194:197], v[98:101]
	v_mfma_f32_16x16x32_bf16 v[90:93], v[178:181], v[194:197], v[90:93]
	v_mfma_f32_16x16x32_bf16 v[82:85], v[170:173], v[202:205], v[82:85]
	v_mfma_f32_16x16x32_bf16 v[74:77], v[178:181], v[202:205], v[74:77]
	v_mfma_f32_16x16x32_bf16 v[70:73], v[170:173], v[210:213], v[70:73]
	v_mfma_f32_16x16x32_bf16 v[66:69], v[178:181], v[210:213], v[66:69]
	v_mfma_f32_16x16x32_bf16 v[114:117], v[174:177], v[190:193], v[114:117]
	v_mfma_f32_16x16x32_bf16 v[106:109], v[182:185], v[190:193], v[106:109]
	v_mfma_f32_16x16x32_bf16 v[98:101], v[174:177], v[198:201], v[98:101]
	v_mfma_f32_16x16x32_bf16 v[90:93], v[182:185], v[198:201], v[90:93]
	v_mfma_f32_16x16x32_bf16 v[82:85], v[174:177], v[206:209], v[82:85]
	v_mfma_f32_16x16x32_bf16 v[74:77], v[182:185], v[206:209], v[74:77]
	v_mfma_f32_16x16x32_bf16 v[70:73], v[174:177], v[214:217], v[70:73]
	v_mfma_f32_16x16x32_bf16 v[66:69], v[182:185], v[214:217], v[66:69]
	s_setprio 0
	s_barrier
	s_mov_b32 m0, s18
	s_mov_b32 s51, s31
	ds_read_b128 v[186:189], v156 offset:16384
	ds_read_b128 v[190:193], v156 offset:17408
	ds_read_b128 v[194:197], v156 offset:18432
	ds_read_b128 v[198:201], v156 offset:19456
	ds_read_b128 v[202:205], v156 offset:20480
	ds_read_b128 v[206:209], v156 offset:21504
	ds_read_b128 v[210:213], v156 offset:22528
	ds_read_b128 v[214:217], v156 offset:23552
	buffer_load_dwordx4 v149, s[48:51], s78 offen lds
	s_mov_b32 m0, s19
	s_add_i32 s80, s78, 0x80000
	buffer_load_dwordx4 v151, s[48:51], s78 offen lds
	s_mov_b32 m0, s22
	s_nop 0
	buffer_load_dwordx4 v149, s[48:51], s80 offen lds
	s_mov_b32 m0, s23
	s_nop 0
	buffer_load_dwordx4 v151, s[48:51], s80 offen lds
	s_mov_b32 m0, s17
	s_nop 0
	buffer_load_dwordx4 v131, s[44:47], s79 offen lds
	s_mov_b32 m0, s28
	s_nop 0
	buffer_load_dwordx4 v150, s[44:47], s79 offen lds
	s_waitcnt vmcnt(8)
	s_waitcnt lgkmcnt(0)
	s_barrier
	s_setprio 1
	s_waitcnt lgkmcnt(7)
	v_mfma_f32_16x16x32_bf16 v[62:65], v[134:137], v[186:189], v[62:65]
	v_mfma_f32_16x16x32_bf16 v[58:61], v[162:165], v[186:189], v[58:61]
	s_waitcnt lgkmcnt(5)
	v_mfma_f32_16x16x32_bf16 v[54:57], v[134:137], v[194:197], v[54:57]
	v_mfma_f32_16x16x32_bf16 v[46:49], v[162:165], v[194:197], v[46:49]
	s_waitcnt lgkmcnt(3)
	v_mfma_f32_16x16x32_bf16 v[38:41], v[134:137], v[202:205], v[38:41]
	v_mfma_f32_16x16x32_bf16 v[30:33], v[162:165], v[202:205], v[30:33]
	s_waitcnt lgkmcnt(1)
	v_mfma_f32_16x16x32_bf16 v[22:25], v[134:137], v[210:213], v[22:25]
	v_mfma_f32_16x16x32_bf16 v[14:17], v[162:165], v[210:213], v[14:17]
	v_mfma_f32_16x16x32_bf16 v[62:65], v[158:161], v[190:193], v[62:65]
	v_mfma_f32_16x16x32_bf16 v[58:61], v[166:169], v[190:193], v[58:61]
	v_mfma_f32_16x16x32_bf16 v[54:57], v[158:161], v[198:201], v[54:57]
	v_mfma_f32_16x16x32_bf16 v[46:49], v[166:169], v[198:201], v[46:49]
	v_mfma_f32_16x16x32_bf16 v[38:41], v[158:161], v[206:209], v[38:41]
	v_mfma_f32_16x16x32_bf16 v[30:33], v[166:169], v[206:209], v[30:33]
	s_waitcnt lgkmcnt(0)
	v_mfma_f32_16x16x32_bf16 v[22:25], v[158:161], v[214:217], v[22:25]
	v_mfma_f32_16x16x32_bf16 v[14:17], v[166:169], v[214:217], v[14:17]
	s_setprio 0
	s_setprio 1
	v_mfma_f32_16x16x32_bf16 v[50:53], v[170:173], v[186:189], v[50:53]
	v_mfma_f32_16x16x32_bf16 v[42:45], v[178:181], v[186:189], v[42:45]
	v_mfma_f32_16x16x32_bf16 v[34:37], v[170:173], v[194:197], v[34:37]
	v_mfma_f32_16x16x32_bf16 v[26:29], v[178:181], v[194:197], v[26:29]
	v_mfma_f32_16x16x32_bf16 v[18:21], v[170:173], v[202:205], v[18:21]
	v_mfma_f32_16x16x32_bf16 v[10:13], v[178:181], v[202:205], v[10:13]
	v_mfma_f32_16x16x32_bf16 v[6:9], v[170:173], v[210:213], v[6:9]
	v_mfma_f32_16x16x32_bf16 v[2:5], v[178:181], v[210:213], v[2:5]
	v_mfma_f32_16x16x32_bf16 v[50:53], v[174:177], v[190:193], v[50:53]
	v_mfma_f32_16x16x32_bf16 v[42:45], v[182:185], v[190:193], v[42:45]
	v_mfma_f32_16x16x32_bf16 v[34:37], v[174:177], v[198:201], v[34:37]
	v_mfma_f32_16x16x32_bf16 v[26:29], v[182:185], v[198:201], v[26:29]
	v_mfma_f32_16x16x32_bf16 v[18:21], v[174:177], v[206:209], v[18:21]
	v_mfma_f32_16x16x32_bf16 v[10:13], v[182:185], v[206:209], v[10:13]
	v_mfma_f32_16x16x32_bf16 v[6:9], v[174:177], v[214:217], v[6:9]
	v_mfma_f32_16x16x32_bf16 v[2:5], v[182:185], v[214:217], v[2:5]
	s_setprio 0
	s_barrier
	ds_read_b128 v[134:137], v220
	ds_read_b128 v[158:161], v220 offset:1024
	ds_read_b128 v[162:165], v220 offset:2048
	ds_read_b128 v[166:169], v220 offset:3072
	ds_read_b128 v[170:173], v221
	ds_read_b128 v[174:177], v221 offset:1024
	ds_read_b128 v[178:181], v221 offset:2048
	ds_read_b128 v[182:185], v221 offset:3072
	s_add_i32 s79, s79, 0x80000
	s_mov_b32 m0, s29
	ds_read_b128 v[186:189], v156 offset:32768
	ds_read_b128 v[190:193], v156 offset:33792
	ds_read_b128 v[194:197], v156 offset:34816
	ds_read_b128 v[198:201], v156 offset:35840
	ds_read_b128 v[202:205], v156 offset:36864
	ds_read_b128 v[206:209], v156 offset:37888
	ds_read_b128 v[210:213], v156 offset:38912
	ds_read_b128 v[214:217], v156 offset:39936
	buffer_load_dwordx4 v131, s[44:47], s79 offen lds
	s_mov_b32 m0, s34
	s_nop 0
	buffer_load_dwordx4 v150, s[44:47], s79 offen lds
	s_waitcnt vmcnt(8)
	s_waitcnt lgkmcnt(0)
	s_barrier
	s_setprio 1
	s_waitcnt lgkmcnt(7)
	v_mfma_f32_16x16x32_bf16 v[126:129], v[134:137], v[186:189], v[126:129]
	v_mfma_f32_16x16x32_bf16 v[122:125], v[162:165], v[186:189], v[122:125]
	s_waitcnt lgkmcnt(5)
	v_mfma_f32_16x16x32_bf16 v[118:121], v[134:137], v[194:197], v[118:121]
	v_mfma_f32_16x16x32_bf16 v[110:113], v[162:165], v[194:197], v[110:113]
	s_waitcnt lgkmcnt(3)
	v_mfma_f32_16x16x32_bf16 v[102:105], v[134:137], v[202:205], v[102:105]
	v_mfma_f32_16x16x32_bf16 v[94:97], v[162:165], v[202:205], v[94:97]
	s_waitcnt lgkmcnt(1)
	v_mfma_f32_16x16x32_bf16 v[86:89], v[134:137], v[210:213], v[86:89]
	v_mfma_f32_16x16x32_bf16 v[78:81], v[162:165], v[210:213], v[78:81]
	v_mfma_f32_16x16x32_bf16 v[126:129], v[158:161], v[190:193], v[126:129]
	v_mfma_f32_16x16x32_bf16 v[122:125], v[166:169], v[190:193], v[122:125]
	v_mfma_f32_16x16x32_bf16 v[118:121], v[158:161], v[198:201], v[118:121]
	v_mfma_f32_16x16x32_bf16 v[110:113], v[166:169], v[198:201], v[110:113]
	v_mfma_f32_16x16x32_bf16 v[102:105], v[158:161], v[206:209], v[102:105]
	v_mfma_f32_16x16x32_bf16 v[94:97], v[166:169], v[206:209], v[94:97]
	s_waitcnt lgkmcnt(0)
	v_mfma_f32_16x16x32_bf16 v[86:89], v[158:161], v[214:217], v[86:89]
	v_mfma_f32_16x16x32_bf16 v[78:81], v[166:169], v[214:217], v[78:81]
	s_setprio 0
	s_setprio 1
	v_mfma_f32_16x16x32_bf16 v[114:117], v[170:173], v[186:189], v[114:117]
	v_mfma_f32_16x16x32_bf16 v[106:109], v[178:181], v[186:189], v[106:109]
	v_mfma_f32_16x16x32_bf16 v[98:101], v[170:173], v[194:197], v[98:101]
	v_mfma_f32_16x16x32_bf16 v[90:93], v[178:181], v[194:197], v[90:93]
	v_mfma_f32_16x16x32_bf16 v[82:85], v[170:173], v[202:205], v[82:85]
	v_mfma_f32_16x16x32_bf16 v[74:77], v[178:181], v[202:205], v[74:77]
	v_mfma_f32_16x16x32_bf16 v[70:73], v[170:173], v[210:213], v[70:73]
	v_mfma_f32_16x16x32_bf16 v[66:69], v[178:181], v[210:213], v[66:69]
	v_mfma_f32_16x16x32_bf16 v[114:117], v[174:177], v[190:193], v[114:117]
	v_mfma_f32_16x16x32_bf16 v[106:109], v[182:185], v[190:193], v[106:109]
	v_mfma_f32_16x16x32_bf16 v[98:101], v[174:177], v[198:201], v[98:101]
	v_mfma_f32_16x16x32_bf16 v[90:93], v[182:185], v[198:201], v[90:93]
	v_mfma_f32_16x16x32_bf16 v[82:85], v[174:177], v[206:209], v[82:85]
	v_mfma_f32_16x16x32_bf16 v[74:77], v[182:185], v[206:209], v[74:77]
	v_mfma_f32_16x16x32_bf16 v[70:73], v[174:177], v[214:217], v[70:73]
	v_mfma_f32_16x16x32_bf16 v[66:69], v[182:185], v[214:217], v[66:69]
	s_setprio 0
	s_barrier
	s_mov_b32 m0, s35
	s_or_b32 s79, s78, 0x80
	ds_read_b128 v[186:189], v156 offset:49152
	ds_read_b128 v[190:193], v156 offset:50176
	ds_read_b128 v[194:197], v156 offset:51200
	ds_read_b128 v[198:201], v156 offset:52224
	ds_read_b128 v[202:205], v156 offset:53248
	ds_read_b128 v[206:209], v156 offset:54272
	ds_read_b128 v[210:213], v156 offset:55296
	ds_read_b128 v[214:217], v156 offset:56320
	buffer_load_dwordx4 v149, s[48:51], s79 offen lds
	s_mov_b32 m0, s36
	s_add_i32 s78, s78, 0x80080
	buffer_load_dwordx4 v151, s[48:51], s79 offen lds
	s_mov_b32 m0, s41
	s_nop 0
	buffer_load_dwordx4 v149, s[48:51], s78 offen lds
	s_mov_b32 m0, s52
	s_nop 0
	buffer_load_dwordx4 v151, s[48:51], s78 offen lds
	s_mov_b32 m0, s37
	s_nop 0
	buffer_load_dwordx4 v131, s[44:47], s77 offen lds
	s_mov_b32 m0, s40
	s_nop 0
	buffer_load_dwordx4 v150, s[44:47], s77 offen lds
	s_waitcnt vmcnt(8)
	s_waitcnt lgkmcnt(0)
	s_barrier
	s_setprio 1
	s_waitcnt lgkmcnt(7)
	v_mfma_f32_16x16x32_bf16 v[62:65], v[134:137], v[186:189], v[62:65]
	v_mfma_f32_16x16x32_bf16 v[58:61], v[162:165], v[186:189], v[58:61]
	s_waitcnt lgkmcnt(5)
	v_mfma_f32_16x16x32_bf16 v[54:57], v[134:137], v[194:197], v[54:57]
	v_mfma_f32_16x16x32_bf16 v[46:49], v[162:165], v[194:197], v[46:49]
	s_waitcnt lgkmcnt(3)
	v_mfma_f32_16x16x32_bf16 v[38:41], v[134:137], v[202:205], v[38:41]
	v_mfma_f32_16x16x32_bf16 v[30:33], v[162:165], v[202:205], v[30:33]
	s_waitcnt lgkmcnt(1)
	v_mfma_f32_16x16x32_bf16 v[22:25], v[134:137], v[210:213], v[22:25]
	v_mfma_f32_16x16x32_bf16 v[14:17], v[162:165], v[210:213], v[14:17]
	v_mfma_f32_16x16x32_bf16 v[62:65], v[158:161], v[190:193], v[62:65]
	v_mfma_f32_16x16x32_bf16 v[58:61], v[166:169], v[190:193], v[58:61]
	v_mfma_f32_16x16x32_bf16 v[54:57], v[158:161], v[198:201], v[54:57]
	v_mfma_f32_16x16x32_bf16 v[46:49], v[166:169], v[198:201], v[46:49]
	v_mfma_f32_16x16x32_bf16 v[38:41], v[158:161], v[206:209], v[38:41]
	v_mfma_f32_16x16x32_bf16 v[30:33], v[166:169], v[206:209], v[30:33]
	s_waitcnt lgkmcnt(0)
	v_mfma_f32_16x16x32_bf16 v[22:25], v[158:161], v[214:217], v[22:25]
	v_mfma_f32_16x16x32_bf16 v[14:17], v[166:169], v[214:217], v[14:17]
	s_setprio 0
	s_setprio 1
	v_mfma_f32_16x16x32_bf16 v[50:53], v[170:173], v[186:189], v[50:53]
	v_mfma_f32_16x16x32_bf16 v[42:45], v[178:181], v[186:189], v[42:45]
	v_mfma_f32_16x16x32_bf16 v[34:37], v[170:173], v[194:197], v[34:37]
	v_mfma_f32_16x16x32_bf16 v[26:29], v[178:181], v[194:197], v[26:29]
	v_mfma_f32_16x16x32_bf16 v[18:21], v[170:173], v[202:205], v[18:21]
	v_mfma_f32_16x16x32_bf16 v[10:13], v[178:181], v[202:205], v[10:13]
	v_mfma_f32_16x16x32_bf16 v[6:9], v[170:173], v[210:213], v[6:9]
	v_mfma_f32_16x16x32_bf16 v[2:5], v[178:181], v[210:213], v[2:5]
	v_mfma_f32_16x16x32_bf16 v[50:53], v[174:177], v[190:193], v[50:53]
	v_mfma_f32_16x16x32_bf16 v[42:45], v[182:185], v[190:193], v[42:45]
	v_mfma_f32_16x16x32_bf16 v[34:37], v[174:177], v[198:201], v[34:37]
	v_mfma_f32_16x16x32_bf16 v[26:29], v[182:185], v[198:201], v[26:29]
	v_mfma_f32_16x16x32_bf16 v[18:21], v[174:177], v[206:209], v[18:21]
	v_mfma_f32_16x16x32_bf16 v[10:13], v[182:185], v[206:209], v[10:13]
	v_mfma_f32_16x16x32_bf16 v[6:9], v[174:177], v[214:217], v[6:9]
	v_mfma_f32_16x16x32_bf16 v[2:5], v[182:185], v[214:217], v[2:5]
	s_setprio 0
	s_barrier
	s_add_i32 s76, s76, 2
	s_addk_i32 s66, 0x100
	s_addk_i32 s67, 0x100
	s_cmp_gt_u32 s76, 29
	s_cbranch_scc0 .LBB0_816
	s_and_b64 vcc, exec, s[10:11]
	s_cbranch_vccz .LBB0_819
	s_barrier

.LBB0_843:
	s_lshl_b32 s14, s62, 19
	s_and_b64 s[66:67], s[6:7], exec
	s_cselect_b32 s66, s14, s76
	s_lshl_b32 s15, s17, 19
	s_and_b64 s[78:79], s[6:7], exec
	v_mov_b32_e32 v2, 0
	s_cselect_b32 s67, s15, s77
	s_add_i32 s76, s76, 0x40080
	s_addk_i32 s77, 0x100
	s_mov_b32 s78, -2
	v_mov_b32_e32 v3, v2
	v_mov_b32_e32 v4, v2
	v_mov_b32_e32 v5, v2
	v_mov_b32_e32 v6, v2
	v_mov_b32_e32 v7, v2
	v_mov_b32_e32 v8, v2
	v_mov_b32_e32 v9, v2
	v_mov_b32_e32 v18, v2
	v_mov_b32_e32 v19, v2
	v_mov_b32_e32 v20, v2
	v_mov_b32_e32 v21, v2
	v_mov_b32_e32 v22, v2
	v_mov_b32_e32 v23, v2
	v_mov_b32_e32 v24, v2
	v_mov_b32_e32 v25, v2
	v_mov_b32_e32 v34, v2
	v_mov_b32_e32 v35, v2
	v_mov_b32_e32 v36, v2
	v_mov_b32_e32 v37, v2
	v_mov_b32_e32 v38, v2
	v_mov_b32_e32 v39, v2
	v_mov_b32_e32 v40, v2
	v_mov_b32_e32 v41, v2
	v_mov_b32_e32 v50, v2
	v_mov_b32_e32 v51, v2
	v_mov_b32_e32 v52, v2
	v_mov_b32_e32 v53, v2
	v_mov_b32_e32 v54, v2
	v_mov_b32_e32 v55, v2
	v_mov_b32_e32 v56, v2
	v_mov_b32_e32 v57, v2
	v_mov_b32_e32 v10, v2
	v_mov_b32_e32 v11, v2
	v_mov_b32_e32 v12, v2
	v_mov_b32_e32 v13, v2
	v_mov_b32_e32 v14, v2
	v_mov_b32_e32 v15, v2
	v_mov_b32_e32 v16, v2
	v_mov_b32_e32 v17, v2
	v_mov_b32_e32 v26, v2
	v_mov_b32_e32 v27, v2
	v_mov_b32_e32 v28, v2
	v_mov_b32_e32 v29, v2
	v_mov_b32_e32 v30, v2
	v_mov_b32_e32 v31, v2
	v_mov_b32_e32 v32, v2
	v_mov_b32_e32 v33, v2
	v_mov_b32_e32 v42, v2
	v_mov_b32_e32 v43, v2
	v_mov_b32_e32 v44, v2
	v_mov_b32_e32 v45, v2
	v_mov_b32_e32 v46, v2
	v_mov_b32_e32 v47, v2
	v_mov_b32_e32 v48, v2
	v_mov_b32_e32 v49, v2
	v_mov_b32_e32 v58, v2
	v_mov_b32_e32 v59, v2
	v_mov_b32_e32 v60, v2
	v_mov_b32_e32 v61, v2
	v_mov_b32_e32 v62, v2
	v_mov_b32_e32 v63, v2
	v_mov_b32_e32 v64, v2
	v_mov_b32_e32 v65, v2
	v_mov_b32_e32 v66, v2
	v_mov_b32_e32 v67, v2
	v_mov_b32_e32 v68, v2
	v_mov_b32_e32 v69, v2
	v_mov_b32_e32 v70, v2
	v_mov_b32_e32 v71, v2
	v_mov_b32_e32 v72, v2
	v_mov_b32_e32 v73, v2
	v_mov_b32_e32 v82, v2
	v_mov_b32_e32 v83, v2
	v_mov_b32_e32 v84, v2
	v_mov_b32_e32 v85, v2
	v_mov_b32_e32 v86, v2
	v_mov_b32_e32 v87, v2
	v_mov_b32_e32 v88, v2
	v_mov_b32_e32 v89, v2
	v_mov_b32_e32 v98, v2
	v_mov_b32_e32 v99, v2
	v_mov_b32_e32 v100, v2
	v_mov_b32_e32 v101, v2
	v_mov_b32_e32 v102, v2
	v_mov_b32_e32 v103, v2
	v_mov_b32_e32 v104, v2
	v_mov_b32_e32 v105, v2
	v_mov_b32_e32 v114, v2
	v_mov_b32_e32 v115, v2
	v_mov_b32_e32 v116, v2
	v_mov_b32_e32 v117, v2
	v_mov_b32_e32 v118, v2
	v_mov_b32_e32 v119, v2
	v_mov_b32_e32 v120, v2
	v_mov_b32_e32 v121, v2
	v_mov_b32_e32 v74, v2
	v_mov_b32_e32 v75, v2
	v_mov_b32_e32 v76, v2
	v_mov_b32_e32 v77, v2
	v_mov_b32_e32 v78, v2
	v_mov_b32_e32 v79, v2
	v_mov_b32_e32 v80, v2
	v_mov_b32_e32 v81, v2
	v_mov_b32_e32 v90, v2
	v_mov_b32_e32 v91, v2
	v_mov_b32_e32 v92, v2
	v_mov_b32_e32 v93, v2
	v_mov_b32_e32 v94, v2
	v_mov_b32_e32 v95, v2
	v_mov_b32_e32 v96, v2
	v_mov_b32_e32 v97, v2
	v_mov_b32_e32 v106, v2
	v_mov_b32_e32 v107, v2
	v_mov_b32_e32 v108, v2
	v_mov_b32_e32 v109, v2
	v_mov_b32_e32 v110, v2
	v_mov_b32_e32 v111, v2
	v_mov_b32_e32 v112, v2
	v_mov_b32_e32 v113, v2
	v_mov_b32_e32 v138, v2
	v_mov_b32_e32 v139, v2
	v_mov_b32_e32 v140, v2
	v_mov_b32_e32 v141, v2
	v_mov_b32_e32 v142, v2
	v_mov_b32_e32 v143, v2
	v_mov_b32_e32 v144, v2
	v_mov_b32_e32 v145, v2
	v_add_u32_e32 v218, 0x10000, v159
	v_add_u32_e32 v219, 0x14000, v159
	v_add_u32_e32 v220, 0x18000, v159
	v_add_u32_e32 v221, 0x1c000, v159
.LBB0_844:
	ds_read_b128 v[122:125], v218
	ds_read_b128 v[126:129], v218 offset:1024
	ds_read_b128 v[130:133], v218 offset:2048
	ds_read_b128 v[134:137], v218 offset:3072
	ds_read_b128 v[162:165], v219
	ds_read_b128 v[166:169], v219 offset:1024
	ds_read_b128 v[170:173], v219 offset:2048
	ds_read_b128 v[174:177], v219 offset:3072
	s_add_i32 s55, s76, 0xfffc0080
	s_cmp_eq_u32 s78, 12
	s_cselect_b32 s82, s66, s55
	s_cselect_b32 s80, s67, s77
	s_or_b32 s79, s82, 0x80
	s_mov_b32 m0, s59
	ds_read_b128 v[178:181], v160
	ds_read_b128 v[182:185], v160 offset:1024
	ds_read_b128 v[186:189], v160 offset:2048
	ds_read_b128 v[190:193], v160 offset:3072
	ds_read_b128 v[194:197], v160 offset:4096
	ds_read_b128 v[198:201], v160 offset:5120
	ds_read_b128 v[202:205], v160 offset:6144
	ds_read_b128 v[206:209], v160 offset:7168
	buffer_load_dwordx4 v153, s[28:31], s76 offen lds
	s_mov_b32 m0, s60
	s_nop 0
	buffer_load_dwordx4 v155, s[28:31], s76 offen lds
	s_waitcnt vmcnt(8)
	s_waitcnt lgkmcnt(0)
	s_barrier
	s_setprio 1
	s_waitcnt lgkmcnt(0)
	v_mfma_i32_16x16x64_i8 v[142:145], v[122:125], v[178:181], v[142:145]
	v_mfma_i32_16x16x64_i8 v[138:141], v[130:133], v[178:181], v[138:141]
	v_mfma_i32_16x16x64_i8 v[110:113], v[122:125], v[186:189], v[110:113]
	v_mfma_i32_16x16x64_i8 v[106:109], v[130:133], v[186:189], v[106:109]
	v_mfma_i32_16x16x64_i8 v[94:97], v[122:125], v[194:197], v[94:97]
	v_mfma_i32_16x16x64_i8 v[90:93], v[130:133], v[194:197], v[90:93]
	v_mfma_i32_16x16x64_i8 v[78:81], v[122:125], v[202:205], v[78:81]
	v_mfma_i32_16x16x64_i8 v[74:77], v[130:133], v[202:205], v[74:77]
	v_mfma_i32_16x16x64_i8 v[142:145], v[126:129], v[182:185], v[142:145]
	v_mfma_i32_16x16x64_i8 v[138:141], v[134:137], v[182:185], v[138:141]
	v_mfma_i32_16x16x64_i8 v[110:113], v[126:129], v[190:193], v[110:113]
	v_mfma_i32_16x16x64_i8 v[106:109], v[134:137], v[190:193], v[106:109]
	v_mfma_i32_16x16x64_i8 v[94:97], v[126:129], v[198:201], v[94:97]
	v_mfma_i32_16x16x64_i8 v[90:93], v[134:137], v[198:201], v[90:93]
	v_mfma_i32_16x16x64_i8 v[78:81], v[126:129], v[206:209], v[78:81]
	v_mfma_i32_16x16x64_i8 v[74:77], v[134:137], v[206:209], v[74:77]
	s_setprio 0
	s_setprio 1
	v_mfma_i32_16x16x64_i8 v[118:121], v[162:165], v[178:181], v[118:121]
	v_mfma_i32_16x16x64_i8 v[114:117], v[170:173], v[178:181], v[114:117]
	v_mfma_i32_16x16x64_i8 v[102:105], v[162:165], v[186:189], v[102:105]
	v_mfma_i32_16x16x64_i8 v[98:101], v[170:173], v[186:189], v[98:101]
	v_mfma_i32_16x16x64_i8 v[86:89], v[162:165], v[194:197], v[86:89]
	v_mfma_i32_16x16x64_i8 v[82:85], v[170:173], v[194:197], v[82:85]
	v_mfma_i32_16x16x64_i8 v[70:73], v[162:165], v[202:205], v[70:73]
	v_mfma_i32_16x16x64_i8 v[66:69], v[170:173], v[202:205], v[66:69]
	v_mfma_i32_16x16x64_i8 v[118:121], v[166:169], v[182:185], v[118:121]
	v_mfma_i32_16x16x64_i8 v[114:117], v[174:177], v[182:185], v[114:117]
	v_mfma_i32_16x16x64_i8 v[102:105], v[166:169], v[190:193], v[102:105]
	v_mfma_i32_16x16x64_i8 v[98:101], v[174:177], v[190:193], v[98:101]
	v_mfma_i32_16x16x64_i8 v[86:89], v[166:169], v[198:201], v[86:89]
	v_mfma_i32_16x16x64_i8 v[82:85], v[174:177], v[198:201], v[82:85]
	v_mfma_i32_16x16x64_i8 v[70:73], v[166:169], v[206:209], v[70:73]
	v_mfma_i32_16x16x64_i8 v[66:69], v[174:177], v[206:209], v[66:69]
	s_setprio 0
	s_barrier
	s_mov_b32 m0, s34
	s_mov_b32 s55, s31
	ds_read_b128 v[178:181], v160 offset:16384
	ds_read_b128 v[182:185], v160 offset:17408
	ds_read_b128 v[186:189], v160 offset:18432
	ds_read_b128 v[190:193], v160 offset:19456
	ds_read_b128 v[194:197], v160 offset:20480
	ds_read_b128 v[198:201], v160 offset:21504
	ds_read_b128 v[202:205], v160 offset:22528
	ds_read_b128 v[206:209], v160 offset:23552
	buffer_load_dwordx4 v154, s[52:55], s80 offen lds
	s_mov_b32 m0, s35
	s_add_i32 s83, s80, 0x40000
	buffer_load_dwordx4 v156, s[52:55], s80 offen lds
	s_mov_b32 m0, s36
	s_nop 0
	buffer_load_dwordx4 v154, s[52:55], s83 offen lds
	s_mov_b32 m0, s37
	s_nop 0
	buffer_load_dwordx4 v156, s[52:55], s83 offen lds
	s_mov_b32 m0, s23
	s_nop 0
	buffer_load_dwordx4 v153, s[28:31], s82 offen lds
	s_mov_b32 m0, s40
	s_nop 0
	buffer_load_dwordx4 v155, s[28:31], s82 offen lds
	s_waitcnt vmcnt(8)
	s_waitcnt lgkmcnt(0)
	s_barrier
	s_setprio 1
	s_waitcnt lgkmcnt(0)
	v_mfma_i32_16x16x64_i8 v[62:65], v[122:125], v[178:181], v[62:65]
	v_mfma_i32_16x16x64_i8 v[58:61], v[130:133], v[178:181], v[58:61]
	v_mfma_i32_16x16x64_i8 v[46:49], v[122:125], v[186:189], v[46:49]
	v_mfma_i32_16x16x64_i8 v[42:45], v[130:133], v[186:189], v[42:45]
	v_mfma_i32_16x16x64_i8 v[30:33], v[122:125], v[194:197], v[30:33]
	v_mfma_i32_16x16x64_i8 v[26:29], v[130:133], v[194:197], v[26:29]
	v_mfma_i32_16x16x64_i8 v[14:17], v[122:125], v[202:205], v[14:17]
	v_mfma_i32_16x16x64_i8 v[10:13], v[130:133], v[202:205], v[10:13]
	v_mfma_i32_16x16x64_i8 v[62:65], v[126:129], v[182:185], v[62:65]
	v_mfma_i32_16x16x64_i8 v[58:61], v[134:137], v[182:185], v[58:61]
	v_mfma_i32_16x16x64_i8 v[46:49], v[126:129], v[190:193], v[46:49]
	v_mfma_i32_16x16x64_i8 v[42:45], v[134:137], v[190:193], v[42:45]
	v_mfma_i32_16x16x64_i8 v[30:33], v[126:129], v[198:201], v[30:33]
	v_mfma_i32_16x16x64_i8 v[26:29], v[134:137], v[198:201], v[26:29]
	v_mfma_i32_16x16x64_i8 v[14:17], v[126:129], v[206:209], v[14:17]
	v_mfma_i32_16x16x64_i8 v[10:13], v[134:137], v[206:209], v[10:13]
	s_setprio 0
	s_setprio 1
	v_mfma_i32_16x16x64_i8 v[54:57], v[162:165], v[178:181], v[54:57]
	v_mfma_i32_16x16x64_i8 v[50:53], v[170:173], v[178:181], v[50:53]
	v_mfma_i32_16x16x64_i8 v[38:41], v[162:165], v[186:189], v[38:41]
	v_mfma_i32_16x16x64_i8 v[34:37], v[170:173], v[186:189], v[34:37]
	v_mfma_i32_16x16x64_i8 v[22:25], v[162:165], v[194:197], v[22:25]
	v_mfma_i32_16x16x64_i8 v[18:21], v[170:173], v[194:197], v[18:21]
	v_mfma_i32_16x16x64_i8 v[6:9], v[162:165], v[202:205], v[6:9]
	v_mfma_i32_16x16x64_i8 v[2:5], v[170:173], v[202:205], v[2:5]
	v_mfma_i32_16x16x64_i8 v[54:57], v[166:169], v[182:185], v[54:57]
	v_mfma_i32_16x16x64_i8 v[50:53], v[174:177], v[182:185], v[50:53]
	v_mfma_i32_16x16x64_i8 v[38:41], v[166:169], v[190:193], v[38:41]
	v_mfma_i32_16x16x64_i8 v[34:37], v[174:177], v[190:193], v[34:37]
	v_mfma_i32_16x16x64_i8 v[22:25], v[166:169], v[198:201], v[22:25]
	v_mfma_i32_16x16x64_i8 v[18:21], v[174:177], v[198:201], v[18:21]
	v_mfma_i32_16x16x64_i8 v[6:9], v[166:169], v[206:209], v[6:9]
	v_mfma_i32_16x16x64_i8 v[2:5], v[174:177], v[206:209], v[2:5]
	s_setprio 0
	s_barrier
	ds_read_b128 v[122:125], v220
	ds_read_b128 v[126:129], v220 offset:1024
	ds_read_b128 v[130:133], v220 offset:2048
	ds_read_b128 v[134:137], v220 offset:3072
	ds_read_b128 v[162:165], v221
	ds_read_b128 v[166:169], v221 offset:1024
	ds_read_b128 v[170:173], v221 offset:2048
	ds_read_b128 v[174:177], v221 offset:3072
	s_add_i32 s82, s82, 0x40000
	s_mov_b32 m0, s41
	ds_read_b128 v[178:181], v160 offset:32768
	ds_read_b128 v[182:185], v160 offset:33792
	ds_read_b128 v[186:189], v160 offset:34816
	ds_read_b128 v[190:193], v160 offset:35840
	ds_read_b128 v[194:197], v160 offset:36864
	ds_read_b128 v[198:201], v160 offset:37888
	ds_read_b128 v[202:205], v160 offset:38912
	ds_read_b128 v[206:209], v160 offset:39936
	buffer_load_dwordx4 v153, s[28:31], s82 offen lds
	s_mov_b32 m0, s43
	s_nop 0
	buffer_load_dwordx4 v155, s[28:31], s82 offen lds
	s_waitcnt vmcnt(8)
	s_waitcnt lgkmcnt(0)
	s_barrier
	s_setprio 1
	s_waitcnt lgkmcnt(0)
	v_mfma_i32_16x16x64_i8 v[142:145], v[122:125], v[178:181], v[142:145]
	v_mfma_i32_16x16x64_i8 v[138:141], v[130:133], v[178:181], v[138:141]
	v_mfma_i32_16x16x64_i8 v[110:113], v[122:125], v[186:189], v[110:113]
	v_mfma_i32_16x16x64_i8 v[106:109], v[130:133], v[186:189], v[106:109]
	v_mfma_i32_16x16x64_i8 v[94:97], v[122:125], v[194:197], v[94:97]
	v_mfma_i32_16x16x64_i8 v[90:93], v[130:133], v[194:197], v[90:93]
	v_mfma_i32_16x16x64_i8 v[78:81], v[122:125], v[202:205], v[78:81]
	v_mfma_i32_16x16x64_i8 v[74:77], v[130:133], v[202:205], v[74:77]
	v_mfma_i32_16x16x64_i8 v[142:145], v[126:129], v[182:185], v[142:145]
	v_mfma_i32_16x16x64_i8 v[138:141], v[134:137], v[182:185], v[138:141]
	v_mfma_i32_16x16x64_i8 v[110:113], v[126:129], v[190:193], v[110:113]
	v_mfma_i32_16x16x64_i8 v[106:109], v[134:137], v[190:193], v[106:109]
	v_mfma_i32_16x16x64_i8 v[94:97], v[126:129], v[198:201], v[94:97]
	v_mfma_i32_16x16x64_i8 v[90:93], v[134:137], v[198:201], v[90:93]
	v_mfma_i32_16x16x64_i8 v[78:81], v[126:129], v[206:209], v[78:81]
	v_mfma_i32_16x16x64_i8 v[74:77], v[134:137], v[206:209], v[74:77]
	s_setprio 0
	s_setprio 1
	v_mfma_i32_16x16x64_i8 v[118:121], v[162:165], v[178:181], v[118:121]
	v_mfma_i32_16x16x64_i8 v[114:117], v[170:173], v[178:181], v[114:117]
	v_mfma_i32_16x16x64_i8 v[102:105], v[162:165], v[186:189], v[102:105]
	v_mfma_i32_16x16x64_i8 v[98:101], v[170:173], v[186:189], v[98:101]
	v_mfma_i32_16x16x64_i8 v[86:89], v[162:165], v[194:197], v[86:89]
	v_mfma_i32_16x16x64_i8 v[82:85], v[170:173], v[194:197], v[82:85]
	v_mfma_i32_16x16x64_i8 v[70:73], v[162:165], v[202:205], v[70:73]
	v_mfma_i32_16x16x64_i8 v[66:69], v[170:173], v[202:205], v[66:69]
	v_mfma_i32_16x16x64_i8 v[118:121], v[166:169], v[182:185], v[118:121]
	v_mfma_i32_16x16x64_i8 v[114:117], v[174:177], v[182:185], v[114:117]
	v_mfma_i32_16x16x64_i8 v[102:105], v[166:169], v[190:193], v[102:105]
	v_mfma_i32_16x16x64_i8 v[98:101], v[174:177], v[190:193], v[98:101]
	v_mfma_i32_16x16x64_i8 v[86:89], v[166:169], v[198:201], v[86:89]
	v_mfma_i32_16x16x64_i8 v[82:85], v[174:177], v[198:201], v[82:85]
	v_mfma_i32_16x16x64_i8 v[70:73], v[166:169], v[206:209], v[70:73]
	v_mfma_i32_16x16x64_i8 v[66:69], v[174:177], v[206:209], v[66:69]
	s_setprio 0
	s_barrier
	s_mov_b32 m0, s44
	s_or_b32 s82, s80, 0x80
	ds_read_b128 v[178:181], v160 offset:49152
	ds_read_b128 v[182:185], v160 offset:50176
	ds_read_b128 v[186:189], v160 offset:51200
	ds_read_b128 v[190:193], v160 offset:52224
	ds_read_b128 v[194:197], v160 offset:53248
	ds_read_b128 v[198:201], v160 offset:54272
	ds_read_b128 v[202:205], v160 offset:55296
	ds_read_b128 v[206:209], v160 offset:56320
	buffer_load_dwordx4 v154, s[52:55], s82 offen lds
	s_mov_b32 m0, s45
	s_add_i32 s80, s80, 0x40080
	buffer_load_dwordx4 v156, s[52:55], s82 offen lds
	s_mov_b32 m0, s49
	s_nop 0
	buffer_load_dwordx4 v154, s[52:55], s80 offen lds
	s_mov_b32 m0, s51
	s_nop 0
	buffer_load_dwordx4 v156, s[52:55], s80 offen lds
	s_mov_b32 m0, s47
	s_nop 0
	buffer_load_dwordx4 v153, s[28:31], s79 offen lds
	s_mov_b32 m0, s48
	s_nop 0
	buffer_load_dwordx4 v155, s[28:31], s79 offen lds
	s_waitcnt vmcnt(8)
	s_waitcnt lgkmcnt(0)
	s_barrier
	s_setprio 1
	s_waitcnt lgkmcnt(0)
	v_mfma_i32_16x16x64_i8 v[62:65], v[122:125], v[178:181], v[62:65]
	v_mfma_i32_16x16x64_i8 v[58:61], v[130:133], v[178:181], v[58:61]
	v_mfma_i32_16x16x64_i8 v[46:49], v[122:125], v[186:189], v[46:49]
	v_mfma_i32_16x16x64_i8 v[42:45], v[130:133], v[186:189], v[42:45]
	v_mfma_i32_16x16x64_i8 v[30:33], v[122:125], v[194:197], v[30:33]
	v_mfma_i32_16x16x64_i8 v[26:29], v[130:133], v[194:197], v[26:29]
	v_mfma_i32_16x16x64_i8 v[14:17], v[122:125], v[202:205], v[14:17]
	v_mfma_i32_16x16x64_i8 v[10:13], v[130:133], v[202:205], v[10:13]
	v_mfma_i32_16x16x64_i8 v[62:65], v[126:129], v[182:185], v[62:65]
	v_mfma_i32_16x16x64_i8 v[58:61], v[134:137], v[182:185], v[58:61]
	v_mfma_i32_16x16x64_i8 v[46:49], v[126:129], v[190:193], v[46:49]
	v_mfma_i32_16x16x64_i8 v[42:45], v[134:137], v[190:193], v[42:45]
	v_mfma_i32_16x16x64_i8 v[30:33], v[126:129], v[198:201], v[30:33]
	v_mfma_i32_16x16x64_i8 v[26:29], v[134:137], v[198:201], v[26:29]
	v_mfma_i32_16x16x64_i8 v[14:17], v[126:129], v[206:209], v[14:17]
	v_mfma_i32_16x16x64_i8 v[10:13], v[134:137], v[206:209], v[10:13]
	s_setprio 0
	s_setprio 1
	v_mfma_i32_16x16x64_i8 v[54:57], v[162:165], v[178:181], v[54:57]
	v_mfma_i32_16x16x64_i8 v[50:53], v[170:173], v[178:181], v[50:53]
	v_mfma_i32_16x16x64_i8 v[38:41], v[162:165], v[186:189], v[38:41]
	v_mfma_i32_16x16x64_i8 v[34:37], v[170:173], v[186:189], v[34:37]
	v_mfma_i32_16x16x64_i8 v[22:25], v[162:165], v[194:197], v[22:25]
	v_mfma_i32_16x16x64_i8 v[18:21], v[170:173], v[194:197], v[18:21]
	v_mfma_i32_16x16x64_i8 v[6:9], v[162:165], v[202:205], v[6:9]
	v_mfma_i32_16x16x64_i8 v[2:5], v[170:173], v[202:205], v[2:5]
	v_mfma_i32_16x16x64_i8 v[54:57], v[166:169], v[182:185], v[54:57]
	v_mfma_i32_16x16x64_i8 v[50:53], v[174:177], v[182:185], v[50:53]
	v_mfma_i32_16x16x64_i8 v[38:41], v[166:169], v[190:193], v[38:41]
	v_mfma_i32_16x16x64_i8 v[34:37], v[174:177], v[190:193], v[34:37]
	v_mfma_i32_16x16x64_i8 v[22:25], v[166:169], v[198:201], v[22:25]
	v_mfma_i32_16x16x64_i8 v[18:21], v[174:177], v[198:201], v[18:21]
	v_mfma_i32_16x16x64_i8 v[6:9], v[166:169], v[206:209], v[6:9]
	v_mfma_i32_16x16x64_i8 v[2:5], v[174:177], v[206:209], v[2:5]
	s_setprio 0
	s_barrier
	s_add_i32 s78, s78, 2
	s_addk_i32 s76, 0x100
	s_addk_i32 s77, 0x100
	s_cmp_gt_u32 s78, 13
	s_cbranch_scc0 .LBB0_844
	s_and_b64 vcc, exec, s[12:13]
	s_cbranch_vccz .LBB0_847
	s_barrier

.LBB0_1160:
	v_and_b32_e32 v219, 15, v210
	v_and_b32_e32 v2, 48, v210
	v_lshlrev_b32_e32 v3, 2, v210
	s_and_b32 s55, s10, 3
	s_lshl_b32 s19, s83, 13
	v_lshl_or_b32 v2, v219, 6, v2
	v_and_b32_e32 v3, 32, v3
	v_bitop3_b32 v4, v2, s19, v3 bitop3:0xde
	s_lshl_b32 s19, s55, 12
	v_bitop3_b32 v3, s19, v2, v3 bitop3:0xf6
	s_add_i32 s19, s7, 0x18000
	s_or_b32 s53, s6, 0x80
	s_mov_b32 m0, s19
	s_add_i32 s52, s7, 0x1a000
	s_waitcnt vmcnt(2)
	s_barrier
	buffer_load_dwordx4 v131, s[56:59], s53 offen lds
	s_mov_b32 m0, s52
	s_or_b32 s65, s15, 0x80
	buffer_load_dwordx4 v133, s[56:59], s53 offen lds
	s_add_i32 s53, s7, 0x8000
	s_mov_b32 m0, s53
	s_add_i32 s64, s7, 0xa000
	buffer_load_dwordx4 v130, s[44:47], s65 offen lds
	s_mov_b32 m0, s64
	s_add_i32 s76, s7, 0x1e000
	buffer_load_dwordx4 v132, s[44:47], s65 offen lds
	s_add_i32 s65, s7, 0x1c000
	s_or_b32 s47, s6, 0x80080
	s_mov_b32 m0, s65
	v_mov_b32_e32 v2, 0
	buffer_load_dwordx4 v131, s[56:59], s47 offen lds
	s_mov_b32 m0, s76
	v_lshl_or_b32 v218, s83, 6, v219
	buffer_load_dwordx4 v133, s[56:59], s47 offen lds
	s_waitcnt vmcnt(6)
	s_mov_b32 s67, 0x80080
	s_add_i32 s77, s7, 0xc000
	s_add_i32 s78, s7, 0xe000
	s_mov_b32 s79, -2
	v_add_u32_e32 v134, 0, v3
	v_add_u32_e32 v135, 0, v4
	v_mov_b32_e32 v3, v2
	v_mov_b32_e32 v4, v2
	v_mov_b32_e32 v5, v2
	v_mov_b32_e32 v6, v2
	v_mov_b32_e32 v7, v2
	v_mov_b32_e32 v8, v2
	v_mov_b32_e32 v9, v2
	v_mov_b32_e32 v18, v2
	v_mov_b32_e32 v19, v2
	v_mov_b32_e32 v20, v2
	v_mov_b32_e32 v21, v2
	v_mov_b32_e32 v22, v2
	v_mov_b32_e32 v23, v2
	v_mov_b32_e32 v24, v2
	v_mov_b32_e32 v25, v2
	v_mov_b32_e32 v62, v2
	v_mov_b32_e32 v63, v2
	v_mov_b32_e32 v64, v2
	v_mov_b32_e32 v65, v2
	v_mov_b32_e32 v70, v2
	v_mov_b32_e32 v71, v2
	v_mov_b32_e32 v72, v2
	v_mov_b32_e32 v73, v2
	v_mov_b32_e32 v114, v2
	v_mov_b32_e32 v115, v2
	v_mov_b32_e32 v116, v2
	v_mov_b32_e32 v117, v2
	v_mov_b32_e32 v122, v2
	v_mov_b32_e32 v123, v2
	v_mov_b32_e32 v124, v2
	v_mov_b32_e32 v125, v2
	v_mov_b32_e32 v10, v2
	v_mov_b32_e32 v11, v2
	v_mov_b32_e32 v12, v2
	v_mov_b32_e32 v13, v2
	v_mov_b32_e32 v14, v2
	v_mov_b32_e32 v15, v2
	v_mov_b32_e32 v16, v2
	v_mov_b32_e32 v17, v2
	v_mov_b32_e32 v38, v2
	v_mov_b32_e32 v39, v2
	v_mov_b32_e32 v40, v2
	v_mov_b32_e32 v41, v2
	v_mov_b32_e32 v46, v2
	v_mov_b32_e32 v47, v2
	v_mov_b32_e32 v48, v2
	v_mov_b32_e32 v49, v2
	v_mov_b32_e32 v90, v2
	v_mov_b32_e32 v91, v2
	v_mov_b32_e32 v92, v2
	v_mov_b32_e32 v93, v2
	v_mov_b32_e32 v98, v2
	v_mov_b32_e32 v99, v2
	v_mov_b32_e32 v100, v2
	v_mov_b32_e32 v101, v2
	v_mov_b32_e32 v118, v2
	v_mov_b32_e32 v119, v2
	v_mov_b32_e32 v120, v2
	v_mov_b32_e32 v121, v2
	v_mov_b32_e32 v126, v2
	v_mov_b32_e32 v127, v2
	v_mov_b32_e32 v128, v2
	v_mov_b32_e32 v129, v2
	v_mov_b32_e32 v106, v2
	v_mov_b32_e32 v107, v2
	v_mov_b32_e32 v108, v2
	v_mov_b32_e32 v109, v2
	v_mov_b32_e32 v110, v2
	v_mov_b32_e32 v111, v2
	v_mov_b32_e32 v112, v2
	v_mov_b32_e32 v113, v2
	v_mov_b32_e32 v82, v2
	v_mov_b32_e32 v83, v2
	v_mov_b32_e32 v84, v2
	v_mov_b32_e32 v85, v2
	v_mov_b32_e32 v86, v2
	v_mov_b32_e32 v87, v2
	v_mov_b32_e32 v88, v2
	v_mov_b32_e32 v89, v2
	v_mov_b32_e32 v58, v2
	v_mov_b32_e32 v59, v2
	v_mov_b32_e32 v60, v2
	v_mov_b32_e32 v61, v2
	v_mov_b32_e32 v66, v2
	v_mov_b32_e32 v67, v2
	v_mov_b32_e32 v68, v2
	v_mov_b32_e32 v69, v2
	v_mov_b32_e32 v34, v2
	v_mov_b32_e32 v35, v2
	v_mov_b32_e32 v36, v2
	v_mov_b32_e32 v37, v2
	v_mov_b32_e32 v42, v2
	v_mov_b32_e32 v43, v2
	v_mov_b32_e32 v44, v2
	v_mov_b32_e32 v45, v2
	v_mov_b32_e32 v94, v2
	v_mov_b32_e32 v95, v2
	v_mov_b32_e32 v96, v2
	v_mov_b32_e32 v97, v2
	v_mov_b32_e32 v102, v2
	v_mov_b32_e32 v103, v2
	v_mov_b32_e32 v104, v2
	v_mov_b32_e32 v105, v2
	v_mov_b32_e32 v74, v2
	v_mov_b32_e32 v75, v2
	v_mov_b32_e32 v76, v2
	v_mov_b32_e32 v77, v2
	v_mov_b32_e32 v78, v2
	v_mov_b32_e32 v79, v2
	v_mov_b32_e32 v80, v2
	v_mov_b32_e32 v81, v2
	v_mov_b32_e32 v50, v2
	v_mov_b32_e32 v51, v2
	v_mov_b32_e32 v52, v2
	v_mov_b32_e32 v53, v2
	v_mov_b32_e32 v54, v2
	v_mov_b32_e32 v55, v2
	v_mov_b32_e32 v56, v2
	v_mov_b32_e32 v57, v2
	v_mov_b32_e32 v26, v2
	v_mov_b32_e32 v27, v2
	v_mov_b32_e32 v28, v2
	v_mov_b32_e32 v29, v2
	v_mov_b32_e32 v30, v2
	v_mov_b32_e32 v31, v2
	v_mov_b32_e32 v32, v2
	v_mov_b32_e32 v33, v2
	v_add_u32_e32 v203, 0x10000, v134
	v_add_u32_e32 v204, 0x14000, v134
	v_add_u32_e32 v205, 0x18000, v134
	v_add_u32_e32 v206, 0x1c000, v134
	s_barrier
.LBB0_1161:
	ds_read_b128 v[136:139], v203
	ds_read_b128 v[140:143], v203 offset:1024
	ds_read_b128 v[144:147], v203 offset:2048
	ds_read_b128 v[148:151], v203 offset:3072
	ds_read_b128 v[152:155], v204
	ds_read_b128 v[156:159], v204 offset:1024
	ds_read_b128 v[160:163], v204 offset:2048
	ds_read_b128 v[164:167], v204 offset:3072
	s_add_i32 s47, s67, 0xfff80080
	s_cmp_lg_u32 s79, 28
	s_cselect_b32 s88, s47, 0
	s_add_i32 s89, s88, s15
	s_or_b32 s80, s89, 0x80
	s_add_i32 s88, s88, s6
	s_add_i32 s59, s15, s67
	s_mov_b32 s47, s31
	s_mov_b32 m0, s77
	ds_read_b128 v[168:171], v135
	ds_read_b128 v[172:175], v135 offset:1024
	ds_read_b128 v[176:179], v135 offset:2048
	ds_read_b128 v[180:183], v135 offset:3072
	ds_read_b128 v[184:187], v135 offset:4096
	ds_read_b128 v[188:191], v135 offset:5120
	ds_read_b128 v[192:195], v135 offset:6144
	ds_read_b128 v[196:199], v135 offset:7168
	buffer_load_dwordx4 v130, s[44:47], s59 offen lds
	s_mov_b32 m0, s78
	s_nop 0
	buffer_load_dwordx4 v132, s[44:47], s59 offen lds
	s_waitcnt vmcnt(8)
	s_waitcnt lgkmcnt(0)
	s_barrier
	s_setprio 1
	s_waitcnt lgkmcnt(7)
	v_mfma_f32_16x16x32_bf16 v[30:33], v[136:139], v[168:171], v[30:33]
	v_mfma_f32_16x16x32_bf16 v[26:29], v[144:147], v[168:171], v[26:29]
	s_waitcnt lgkmcnt(5)
	v_mfma_f32_16x16x32_bf16 v[54:57], v[136:139], v[176:179], v[54:57]
	v_mfma_f32_16x16x32_bf16 v[50:53], v[144:147], v[176:179], v[50:53]
	s_waitcnt lgkmcnt(3)
	v_mfma_f32_16x16x32_bf16 v[78:81], v[136:139], v[184:187], v[78:81]
	v_mfma_f32_16x16x32_bf16 v[74:77], v[144:147], v[184:187], v[74:77]
	s_waitcnt lgkmcnt(1)
	v_mfma_f32_16x16x32_bf16 v[102:105], v[136:139], v[192:195], v[102:105]
	v_mfma_f32_16x16x32_bf16 v[94:97], v[144:147], v[192:195], v[94:97]
	v_mfma_f32_16x16x32_bf16 v[30:33], v[140:143], v[172:175], v[30:33]
	v_mfma_f32_16x16x32_bf16 v[26:29], v[148:151], v[172:175], v[26:29]
	v_mfma_f32_16x16x32_bf16 v[54:57], v[140:143], v[180:183], v[54:57]
	v_mfma_f32_16x16x32_bf16 v[50:53], v[148:151], v[180:183], v[50:53]
	v_mfma_f32_16x16x32_bf16 v[78:81], v[140:143], v[188:191], v[78:81]
	v_mfma_f32_16x16x32_bf16 v[74:77], v[148:151], v[188:191], v[74:77]
	s_waitcnt lgkmcnt(0)
	v_mfma_f32_16x16x32_bf16 v[102:105], v[140:143], v[196:199], v[102:105]
	v_mfma_f32_16x16x32_bf16 v[94:97], v[148:151], v[196:199], v[94:97]
	s_setprio 0
	s_setprio 1
	v_mfma_f32_16x16x32_bf16 v[42:45], v[152:155], v[168:171], v[42:45]
	v_mfma_f32_16x16x32_bf16 v[34:37], v[160:163], v[168:171], v[34:37]
	v_mfma_f32_16x16x32_bf16 v[66:69], v[152:155], v[176:179], v[66:69]
	v_mfma_f32_16x16x32_bf16 v[58:61], v[160:163], v[176:179], v[58:61]
	v_mfma_f32_16x16x32_bf16 v[86:89], v[152:155], v[184:187], v[86:89]
	v_mfma_f32_16x16x32_bf16 v[82:85], v[160:163], v[184:187], v[82:85]
	v_mfma_f32_16x16x32_bf16 v[110:113], v[152:155], v[192:195], v[110:113]
	v_mfma_f32_16x16x32_bf16 v[106:109], v[160:163], v[192:195], v[106:109]
	v_mfma_f32_16x16x32_bf16 v[42:45], v[156:159], v[172:175], v[42:45]
	v_mfma_f32_16x16x32_bf16 v[34:37], v[164:167], v[172:175], v[34:37]
	v_mfma_f32_16x16x32_bf16 v[66:69], v[156:159], v[180:183], v[66:69]
	v_mfma_f32_16x16x32_bf16 v[58:61], v[164:167], v[180:183], v[58:61]
	v_mfma_f32_16x16x32_bf16 v[86:89], v[156:159], v[188:191], v[86:89]
	v_mfma_f32_16x16x32_bf16 v[82:85], v[164:167], v[188:191], v[82:85]
	v_mfma_f32_16x16x32_bf16 v[110:113], v[156:159], v[196:199], v[110:113]
	v_mfma_f32_16x16x32_bf16 v[106:109], v[164:167], v[196:199], v[106:109]
	s_setprio 0
	s_barrier
	s_mov_b32 m0, s8
	s_mov_b32 s59, s31
	ds_read_b128 v[168:171], v135 offset:16384
	ds_read_b128 v[172:175], v135 offset:17408
	ds_read_b128 v[176:179], v135 offset:18432
	ds_read_b128 v[180:183], v135 offset:19456
	ds_read_b128 v[184:187], v135 offset:20480
	ds_read_b128 v[188:191], v135 offset:21504
	ds_read_b128 v[192:195], v135 offset:22528
	ds_read_b128 v[196:199], v135 offset:23552
	buffer_load_dwordx4 v131, s[56:59], s88 offen lds
	s_mov_b32 m0, s9
	s_add_i32 s90, s88, 0x80000
	buffer_load_dwordx4 v133, s[56:59], s88 offen lds
	s_mov_b32 m0, s13
	s_nop 0
	buffer_load_dwordx4 v131, s[56:59], s90 offen lds
	s_mov_b32 m0, s14
	s_nop 0
	buffer_load_dwordx4 v133, s[56:59], s90 offen lds
	s_mov_b32 m0, s7
	s_nop 0
	buffer_load_dwordx4 v130, s[44:47], s89 offen lds
	s_mov_b32 m0, s16
	s_nop 0
	buffer_load_dwordx4 v132, s[44:47], s89 offen lds
	s_waitcnt vmcnt(8)
	s_waitcnt lgkmcnt(0)
	s_barrier
	s_setprio 1
	s_waitcnt lgkmcnt(7)
	v_mfma_f32_16x16x32_bf16 v[126:129], v[136:139], v[168:171], v[126:129]
	v_mfma_f32_16x16x32_bf16 v[118:121], v[144:147], v[168:171], v[118:121]
	s_waitcnt lgkmcnt(5)
	v_mfma_f32_16x16x32_bf16 v[98:101], v[136:139], v[176:179], v[98:101]
	v_mfma_f32_16x16x32_bf16 v[90:93], v[144:147], v[176:179], v[90:93]
	s_waitcnt lgkmcnt(3)
	v_mfma_f32_16x16x32_bf16 v[46:49], v[136:139], v[184:187], v[46:49]
	v_mfma_f32_16x16x32_bf16 v[38:41], v[144:147], v[184:187], v[38:41]
	s_waitcnt lgkmcnt(1)
	v_mfma_f32_16x16x32_bf16 v[14:17], v[136:139], v[192:195], v[14:17]
	v_mfma_f32_16x16x32_bf16 v[10:13], v[144:147], v[192:195], v[10:13]
	v_mfma_f32_16x16x32_bf16 v[126:129], v[140:143], v[172:175], v[126:129]
	v_mfma_f32_16x16x32_bf16 v[118:121], v[148:151], v[172:175], v[118:121]
	v_mfma_f32_16x16x32_bf16 v[98:101], v[140:143], v[180:183], v[98:101]
	v_mfma_f32_16x16x32_bf16 v[90:93], v[148:151], v[180:183], v[90:93]
	v_mfma_f32_16x16x32_bf16 v[46:49], v[140:143], v[188:191], v[46:49]
	v_mfma_f32_16x16x32_bf16 v[38:41], v[148:151], v[188:191], v[38:41]
	s_waitcnt lgkmcnt(0)
	v_mfma_f32_16x16x32_bf16 v[14:17], v[140:143], v[196:199], v[14:17]
	v_mfma_f32_16x16x32_bf16 v[10:13], v[148:151], v[196:199], v[10:13]
	s_setprio 0
	s_setprio 1
	v_mfma_f32_16x16x32_bf16 v[122:125], v[152:155], v[168:171], v[122:125]
	v_mfma_f32_16x16x32_bf16 v[114:117], v[160:163], v[168:171], v[114:117]
	v_mfma_f32_16x16x32_bf16 v[70:73], v[152:155], v[176:179], v[70:73]
	v_mfma_f32_16x16x32_bf16 v[62:65], v[160:163], v[176:179], v[62:65]
	v_mfma_f32_16x16x32_bf16 v[22:25], v[152:155], v[184:187], v[22:25]
	v_mfma_f32_16x16x32_bf16 v[18:21], v[160:163], v[184:187], v[18:21]
	v_mfma_f32_16x16x32_bf16 v[6:9], v[152:155], v[192:195], v[6:9]
	v_mfma_f32_16x16x32_bf16 v[2:5], v[160:163], v[192:195], v[2:5]
	v_mfma_f32_16x16x32_bf16 v[122:125], v[156:159], v[172:175], v[122:125]
	v_mfma_f32_16x16x32_bf16 v[114:117], v[164:167], v[172:175], v[114:117]
	v_mfma_f32_16x16x32_bf16 v[70:73], v[156:159], v[180:183], v[70:73]
	v_mfma_f32_16x16x32_bf16 v[62:65], v[164:167], v[180:183], v[62:65]
	v_mfma_f32_16x16x32_bf16 v[22:25], v[156:159], v[188:191], v[22:25]
	v_mfma_f32_16x16x32_bf16 v[18:21], v[164:167], v[188:191], v[18:21]
	v_mfma_f32_16x16x32_bf16 v[6:9], v[156:159], v[196:199], v[6:9]
	v_mfma_f32_16x16x32_bf16 v[2:5], v[164:167], v[196:199], v[2:5]
	s_setprio 0
	s_barrier
	ds_read_b128 v[136:139], v205
	ds_read_b128 v[140:143], v205 offset:1024
	ds_read_b128 v[144:147], v205 offset:2048
	ds_read_b128 v[148:151], v205 offset:3072
	ds_read_b128 v[152:155], v206
	ds_read_b128 v[156:159], v206 offset:1024
	ds_read_b128 v[160:163], v206 offset:2048
	ds_read_b128 v[164:167], v206 offset:3072
	s_add_i32 s89, s89, 0x80000
	s_mov_b32 m0, s17
	ds_read_b128 v[168:171], v135 offset:32768
	ds_read_b128 v[172:175], v135 offset:33792
	ds_read_b128 v[176:179], v135 offset:34816
	ds_read_b128 v[180:183], v135 offset:35840
	ds_read_b128 v[184:187], v135 offset:36864
	ds_read_b128 v[188:191], v135 offset:37888
	ds_read_b128 v[192:195], v135 offset:38912
	ds_read_b128 v[196:199], v135 offset:39936
	buffer_load_dwordx4 v130, s[44:47], s89 offen lds
	s_mov_b32 m0, s18
	s_nop 0
	buffer_load_dwordx4 v132, s[44:47], s89 offen lds
	s_waitcnt vmcnt(8)
	s_waitcnt lgkmcnt(0)
	s_barrier
	s_setprio 1
	s_waitcnt lgkmcnt(7)
	v_mfma_f32_16x16x32_bf16 v[30:33], v[136:139], v[168:171], v[30:33]
	v_mfma_f32_16x16x32_bf16 v[26:29], v[144:147], v[168:171], v[26:29]
	s_waitcnt lgkmcnt(5)
	v_mfma_f32_16x16x32_bf16 v[54:57], v[136:139], v[176:179], v[54:57]
	v_mfma_f32_16x16x32_bf16 v[50:53], v[144:147], v[176:179], v[50:53]
	s_waitcnt lgkmcnt(3)
	v_mfma_f32_16x16x32_bf16 v[78:81], v[136:139], v[184:187], v[78:81]
	v_mfma_f32_16x16x32_bf16 v[74:77], v[144:147], v[184:187], v[74:77]
	s_waitcnt lgkmcnt(1)
	v_mfma_f32_16x16x32_bf16 v[102:105], v[136:139], v[192:195], v[102:105]
	v_mfma_f32_16x16x32_bf16 v[94:97], v[144:147], v[192:195], v[94:97]
	v_mfma_f32_16x16x32_bf16 v[30:33], v[140:143], v[172:175], v[30:33]
	v_mfma_f32_16x16x32_bf16 v[26:29], v[148:151], v[172:175], v[26:29]
	v_mfma_f32_16x16x32_bf16 v[54:57], v[140:143], v[180:183], v[54:57]
	v_mfma_f32_16x16x32_bf16 v[50:53], v[148:151], v[180:183], v[50:53]
	v_mfma_f32_16x16x32_bf16 v[78:81], v[140:143], v[188:191], v[78:81]
	v_mfma_f32_16x16x32_bf16 v[74:77], v[148:151], v[188:191], v[74:77]
	s_waitcnt lgkmcnt(0)
	v_mfma_f32_16x16x32_bf16 v[102:105], v[140:143], v[196:199], v[102:105]
	v_mfma_f32_16x16x32_bf16 v[94:97], v[148:151], v[196:199], v[94:97]
	s_setprio 0
	s_setprio 1
	v_mfma_f32_16x16x32_bf16 v[42:45], v[152:155], v[168:171], v[42:45]
	v_mfma_f32_16x16x32_bf16 v[34:37], v[160:163], v[168:171], v[34:37]
	v_mfma_f32_16x16x32_bf16 v[66:69], v[152:155], v[176:179], v[66:69]
	v_mfma_f32_16x16x32_bf16 v[58:61], v[160:163], v[176:179], v[58:61]
	v_mfma_f32_16x16x32_bf16 v[86:89], v[152:155], v[184:187], v[86:89]
	v_mfma_f32_16x16x32_bf16 v[82:85], v[160:163], v[184:187], v[82:85]
	v_mfma_f32_16x16x32_bf16 v[110:113], v[152:155], v[192:195], v[110:113]
	v_mfma_f32_16x16x32_bf16 v[106:109], v[160:163], v[192:195], v[106:109]
	v_mfma_f32_16x16x32_bf16 v[42:45], v[156:159], v[172:175], v[42:45]
	v_mfma_f32_16x16x32_bf16 v[34:37], v[164:167], v[172:175], v[34:37]
	v_mfma_f32_16x16x32_bf16 v[66:69], v[156:159], v[180:183], v[66:69]
	v_mfma_f32_16x16x32_bf16 v[58:61], v[164:167], v[180:183], v[58:61]
	v_mfma_f32_16x16x32_bf16 v[86:89], v[156:159], v[188:191], v[86:89]
	v_mfma_f32_16x16x32_bf16 v[82:85], v[164:167], v[188:191], v[82:85]
	v_mfma_f32_16x16x32_bf16 v[110:113], v[156:159], v[196:199], v[110:113]
	v_mfma_f32_16x16x32_bf16 v[106:109], v[164:167], v[196:199], v[106:109]
	s_setprio 0
	s_barrier
	s_mov_b32 m0, s19
	s_or_b32 s89, s88, 0x80
	ds_read_b128 v[168:171], v135 offset:49152
	ds_read_b128 v[172:175], v135 offset:50176
	ds_read_b128 v[176:179], v135 offset:51200
	ds_read_b128 v[180:183], v135 offset:52224
	ds_read_b128 v[184:187], v135 offset:53248
	ds_read_b128 v[188:191], v135 offset:54272
	ds_read_b128 v[192:195], v135 offset:55296
	ds_read_b128 v[196:199], v135 offset:56320
	buffer_load_dwordx4 v131, s[56:59], s89 offen lds
	s_mov_b32 m0, s52
	s_add_i32 s88, s88, 0x80080
	buffer_load_dwordx4 v133, s[56:59], s89 offen lds
	s_mov_b32 m0, s65
	s_nop 0
	buffer_load_dwordx4 v131, s[56:59], s88 offen lds
	s_mov_b32 m0, s76
	s_nop 0
	buffer_load_dwordx4 v133, s[56:59], s88 offen lds
	s_mov_b32 m0, s53
	s_nop 0
	buffer_load_dwordx4 v130, s[44:47], s80 offen lds
	s_mov_b32 m0, s64
	s_nop 0
	buffer_load_dwordx4 v132, s[44:47], s80 offen lds
	s_waitcnt vmcnt(8)
	s_waitcnt lgkmcnt(0)
	s_barrier
	s_setprio 1
	s_waitcnt lgkmcnt(7)
	v_mfma_f32_16x16x32_bf16 v[126:129], v[136:139], v[168:171], v[126:129]
	v_mfma_f32_16x16x32_bf16 v[118:121], v[144:147], v[168:171], v[118:121]
	s_waitcnt lgkmcnt(5)
	v_mfma_f32_16x16x32_bf16 v[98:101], v[136:139], v[176:179], v[98:101]
	v_mfma_f32_16x16x32_bf16 v[90:93], v[144:147], v[176:179], v[90:93]
	s_waitcnt lgkmcnt(3)
	v_mfma_f32_16x16x32_bf16 v[46:49], v[136:139], v[184:187], v[46:49]
	v_mfma_f32_16x16x32_bf16 v[38:41], v[144:147], v[184:187], v[38:41]
	s_waitcnt lgkmcnt(1)
	v_mfma_f32_16x16x32_bf16 v[14:17], v[136:139], v[192:195], v[14:17]
	v_mfma_f32_16x16x32_bf16 v[10:13], v[144:147], v[192:195], v[10:13]
	v_mfma_f32_16x16x32_bf16 v[126:129], v[140:143], v[172:175], v[126:129]
	v_mfma_f32_16x16x32_bf16 v[118:121], v[148:151], v[172:175], v[118:121]
	v_mfma_f32_16x16x32_bf16 v[98:101], v[140:143], v[180:183], v[98:101]
	v_mfma_f32_16x16x32_bf16 v[90:93], v[148:151], v[180:183], v[90:93]
	v_mfma_f32_16x16x32_bf16 v[46:49], v[140:143], v[188:191], v[46:49]
	v_mfma_f32_16x16x32_bf16 v[38:41], v[148:151], v[188:191], v[38:41]
	s_waitcnt lgkmcnt(0)
	v_mfma_f32_16x16x32_bf16 v[14:17], v[140:143], v[196:199], v[14:17]
	v_mfma_f32_16x16x32_bf16 v[10:13], v[148:151], v[196:199], v[10:13]
	s_setprio 0
	s_setprio 1
	v_mfma_f32_16x16x32_bf16 v[122:125], v[152:155], v[168:171], v[122:125]
	v_mfma_f32_16x16x32_bf16 v[114:117], v[160:163], v[168:171], v[114:117]
	v_mfma_f32_16x16x32_bf16 v[70:73], v[152:155], v[176:179], v[70:73]
	v_mfma_f32_16x16x32_bf16 v[62:65], v[160:163], v[176:179], v[62:65]
	v_mfma_f32_16x16x32_bf16 v[22:25], v[152:155], v[184:187], v[22:25]
	v_mfma_f32_16x16x32_bf16 v[18:21], v[160:163], v[184:187], v[18:21]
	v_mfma_f32_16x16x32_bf16 v[6:9], v[152:155], v[192:195], v[6:9]
	v_mfma_f32_16x16x32_bf16 v[2:5], v[160:163], v[192:195], v[2:5]
	v_mfma_f32_16x16x32_bf16 v[122:125], v[156:159], v[172:175], v[122:125]
	v_mfma_f32_16x16x32_bf16 v[114:117], v[164:167], v[172:175], v[114:117]
	v_mfma_f32_16x16x32_bf16 v[70:73], v[156:159], v[180:183], v[70:73]
	v_mfma_f32_16x16x32_bf16 v[62:65], v[164:167], v[180:183], v[62:65]
	v_mfma_f32_16x16x32_bf16 v[22:25], v[156:159], v[188:191], v[22:25]
	v_mfma_f32_16x16x32_bf16 v[18:21], v[164:167], v[188:191], v[18:21]
	v_mfma_f32_16x16x32_bf16 v[6:9], v[156:159], v[196:199], v[6:9]
	v_mfma_f32_16x16x32_bf16 v[2:5], v[164:167], v[196:199], v[2:5]
	s_setprio 0
	s_barrier
	s_add_i32 s79, s79, 2
	s_addk_i32 s67, 0x100
	s_cmp_lt_u32 s79, 30
	s_cbranch_scc1 .LBB0_1161
	s_waitcnt vmcnt(0)
	s_cmpk_gt_u32 s66, 0xff
	s_cbranch_scc1 .LBB0_1164
	s_barrier
